# fused sub3->sub4 wait: XCD-local acquire (no L2 invalidate) when the census shows all 8 producers of the row panel are on this XCD
# speedup vs baseline: 1.0089x; 1.0038x over previous
.LBB0_148:
	s_and_b32 s0, s14, -8
	s_or_b32 s0, s0, s15
	s_load_dword s22, s[96:97], 0x0
	s_waitcnt lgkmcnt(0)
	s_cmp_eq_u32 s22, 0x200
	s_cbranch_scc0 .Lgw_skipall
	v_cmp_eq_u32_e64 s[22:23], 0, v124
	s_and_saveexec_b64 s[20:21], s[22:23]
	s_cbranch_execz .Lgw_done
	s_lshl_b32 s22, s0, 2
	s_lshl_b32 s23, s12, 8
	s_add_i32 s22, s22, s23
	s_addk_i32 s22, 0x1404
	v_mov_b32_e32 v0, s22
	s_lshl_b32 s1, s0, 2
	s_addk_i32 s1, 0x100
	v_mov_b32_e32 v1, s1
	global_load_dword v1, v1, s[4:5] sc1
	s_getreg_b32 s1, hwreg(HW_REG_XCC_ID, 0, 4)
	s_lshl_b32 s1, s1, 2
	s_lshl_b32 s1, 8, s1
	s_waitcnt vmcnt(0)
	v_readfirstlane_b32 s22, v1
	s_sub_i32 s1, s1, s22
	s_mov_b32 s23, 0

.Lgw_got:
	s_cmp_eq_u32 s1, 0
	s_cbranch_scc1 .Lgw_loc
	buffer_inv sc1
	s_branch .Lgw_inv
.Lgw_loc:
	buffer_inv sc0
.Lgw_inv:
	s_waitcnt vmcnt(0)
.Lgw_done:
	s_or_b64 exec, exec, s[20:21]
	s_barrier
